# v12 with vmcnt(0) kept before the copies of row group 7's prefetched rotary tables (loads and stores can complete out of order)
# speedup vs baseline: 1.0052x; 1.0052x over previous
;     DI void operator()(const pg8::f32x4 (&acc)[2][2][4][2], const pg8::Unit& u, int wr, int wc, int fr, int fq) const {
;     ...
;                 if ((att || ret) && row < M_LAT) {
;                     rot = true;
;                     const int s = row & 4095;
;                     const f32x2* tp;
;                     if (att) { const int pos = (wc & 1) ? (s & 63) : (s >> 6); tp = tatt + pos * 16 + 4 * fq; }
;                     else { tp = tret + (size_t)s * 32 + 16 * (wc & 1) + 4 * fq; }
;                     const f32x4 t0 = *(const f32x4*)tp, t1 = *(const f32x4*)(tp + 2);
;                     cs[0] = (f32x2){t0.x, t0.y}; cs[1] = (f32x2){t0.z, t0.w}; cs[2] = (f32x2){t1.x, t1.y}; cs[3] = (f32x2){t1.z, t1.w};
.LBB0_172:
	s_or_b64 exec, exec, s[28:29]
	v_pk_mul_f32 v[150:151], v[164:165], v[170:171]
	s_nop 0
	v_cvt_pk_bf16_f32 v170, v150, v151
	v_pk_mul_f32 v[150:151], v[164:165], v[172:173]
	s_nop 0
	v_cvt_pk_bf16_f32 v171, v150, v151
	v_pk_mul_f32 v[150:151], v[164:165], v[174:175]
	s_nop 0
	v_cvt_pk_bf16_f32 v172, v150, v151
	v_pk_mul_f32 v[150:151], v[164:165], v[176:177]
	s_nop 0
	v_cvt_pk_bf16_f32 v173, v150, v151
	global_store_dwordx4 v[168:169], v[170:173], off offset:256
	s_movk_i32 s0, 0x7f50
	v_cmp_gt_i32_e64 s[0:1], s0, v180
	v_add_u32_e32 v174, 0xb0, v180
	s_and_b64 s[0:1], s[2:3], s[0:1]
	s_and_saveexec_b64 s[2:3], s[0:1]
	s_cbranch_execz .LBB0_174
	s_waitcnt vmcnt(0)
	v_bfe_u32 v129, v174, 6, 6
	v_and_b32_e32 v128, 0xfff, v174
	v_cndmask_b32_e64 v129, v159, v129, s[6:7]
	v_lshlrev_b32_e32 v129, 4, v129
	v_lshlrev_b32_e32 v128, 5, v128
	v_cndmask_b32_e32 v128, v128, v129, vcc
	s_and_b64 s[28:29], vcc, exec
	s_cselect_b32 s29, s41, s49
	s_cselect_b32 s28, s40, s48
	v_lshlrev_b32_e32 v128, 3, v128
	v_mov_b32_e32 v129, v147
	v_lshl_add_u64 v[128:129], s[28:29], 0, v[128:129]
	v_mov_b32_e32 v167, v147
	v_lshl_add_u64 v[132:133], v[128:129], 0, v[166:167]
	v_mov_b32_e32 v128, v194
	v_mov_b32_e32 v129, v195
	v_mov_b32_e32 v130, v196
	v_mov_b32_e32 v131, v197
	s_nop 0
	v_mov_b32_e32 v132, v190
	v_mov_b32_e32 v133, v191
	v_mov_b32_e32 v134, v192
	v_mov_b32_e32 v135, v193
